# GEMM mainloops: static s_setprio 1 for the wave half that enters first (wr==0) instead of the late half, toggling removed; direction check of the static-priority lever
# speedup vs baseline: 1.0066x; 1.0066x over previous
.LBB0_101:
	v_ashrrev_i32_e32 v0, 31, v158
	v_lshrrev_b32_e32 v0, 26, v0
	v_add_u32_e32 v0, v158, v0
	s_waitcnt vmcnt(0)
	v_ashrrev_i32_e32 v10, 6, v0
	v_bfe_i32 v0, v158, 27, 1
	v_lshlrev_b32_e32 v2, 4, v158
	v_lshrrev_b32_e32 v0, 22, v0
	v_add_u32_e32 v0, v2, v0
	v_and_b32_e32 v0, 0xfffffc00, v0
	v_sub_u32_e32 v0, v2, v0
	v_lshrrev_b32_e32 v3, 4, v0
	v_bitop3_b32 v3, v3, v0, 32 bitop3:0x6c
	v_ashrrev_i32_e32 v0, 31, v0
	v_lshrrev_b32_e32 v0, 26, v0
	v_lshlrev_b32_e32 v4, 3, v10
	v_add_u32_e32 v0, v3, v0
	v_and_b32_e32 v4, -16, v4
	v_ashrrev_i32_e32 v11, 6, v0
	s_waitcnt lgkmcnt(0)
	s_add_u32 s25, s2, 0xb580000
	v_add_u32_e32 v0, v11, v4
	v_lshlrev_b32_e32 v4, 5, v10
	s_addc_u32 s26, s3, 0
	s_mul_i32 s13, s44, 0x580000
	v_and_b32_e32 v12, 32, v4
	v_mul_i32_i24_e32 v4, 64, v11
	s_mul_hi_i32 s11, s44, 0x580000
	s_add_u32 s27, s8, s13
	v_sub_u32_e32 v3, v3, v4
	s_addc_u32 s28, s9, s11
	v_ashrrev_i16_sdwa v3, v207, sext(v3) dst_sel:DWORD dst_unused:UNUSED_PAD src0_sel:DWORD src1_sel:BYTE_0
	v_lshlrev_b32_e32 v4, 1, v0
	v_lshrrev_b32_e32 v5, 2, v0
	v_and_b32_e32 v6, 3, v11
	s_mov_b32 s9, 0xffffe0
	v_bfe_i32 v13, v3, 0, 16
	v_and_b32_e32 v4, 24, v4
	v_and_b32_e32 v5, 4, v5
	v_and_or_b32 v6, v0, s9, v6
	v_add_u32_e32 v3, v12, v13
	v_or3_b32 v4, v6, v5, v4
	v_mul_lo_u32 v0, v0, s71
	v_add_lshl_u32 v130, v3, v0, 1
	v_mul_u32_u24_e32 v0, 0xb00, v4
	v_add_u32_e32 v2, 0x2000, v2
	v_add_lshl_u32 v0, v0, v3, 1
	v_ashrrev_i32_e32 v3, 31, v2
	v_lshrrev_b32_e32 v3, 22, v3
	s_add_i32 s10, s12, s10
	v_add_u32_e32 v3, v2, v3
	s_ashr_i32 s11, s10, 31
	v_ashrrev_i32_e32 v14, 10, v3
	s_lshr_b32 s11, s11, 27
	v_mul_i32_i24_e32 v3, 0x400, v14
	s_add_i32 s11, s10, s11
	v_sub_u32_e32 v2, v2, v3
	s_ashr_i32 s12, s11, 5
	s_and_b32 s11, s11, 0xffe0
	v_lshrrev_b32_e32 v3, 4, v2
	s_sub_i32 s11, s10, s11
	v_bitop3_b32 v2, v3, v2, 32 bitop3:0x6c
	s_bfe_i32 s10, s11, 0x80000
	v_ashrrev_i32_e32 v4, 31, v2
	s_bfe_u32 s10, s10, 0x3000c
	v_lshrrev_b32_e32 v4, 26, v4
	s_add_i32 s13, s11, s10
	v_lshlrev_b32_e32 v3, 3, v14
	v_add_u32_e32 v4, v2, v4
	s_bfe_i32 s10, s13, 0x80000
	s_and_b32 s13, s13, 0xf8
	v_and_b32_e32 v3, -16, v3
	v_ashrrev_i32_e32 v15, 6, v4
	s_sext_i32_i16 s14, s10
	s_sub_i32 s11, s11, s13
	s_ashr_i32 s8, s1, 6
	v_add_u32_e32 v3, v15, v3
	v_and_b32_e32 v4, 0xc0, v4
	v_and_b32_e32 v6, 3, v15
	s_lshl_b32 s12, s12, 3
	s_sext_i32_i8 s11, s11
	s_ashr_i32 s13, s14, 3
	v_lshlrev_b32_e32 v5, 5, v14
	v_sub_u32_e32 v2, v2, v4
	v_and_or_b32 v6, v3, s9, v6
	s_ashr_i32 s9, s1, 8
	s_lshl_b32 s29, s8, 10
	s_lshr_b32 s10, s14, 3
	s_add_i32 s46, s12, s11
	s_mul_hi_i32 s15, s13, 0x160000
	s_mul_i32 s13, s13, 0x160000
	v_and_b32_e32 v16, 32, v5
	v_ashrrev_i16_sdwa v2, v207, sext(v2) dst_sel:DWORD dst_unused:UNUSED_PAD src0_sel:DWORD src1_sel:BYTE_0
	v_lshlrev_b32_e32 v4, 1, v3
	v_lshrrev_b32_e32 v5, 2, v3
	s_add_u32 s14, s27, s13
	v_bfe_i32 v17, v2, 0, 16
	v_and_b32_e32 v4, 24, v4
	v_and_b32_e32 v5, 4, v5
	s_addc_u32 s15, s28, s15
	s_add_i32 s30, s29, 0
	v_add_u32_e32 v2, v16, v17
	v_or3_b32 v4, v6, v5, v4
	v_mul_lo_u32 v3, v3, s71
	s_add_i32 m0, s30, 0x10000
	v_add_lshl_u32 v132, v2, v3, 1
	v_mul_u32_u24_e32 v3, 0xb00, v4
	s_mul_i32 s12, s46, 0x160000
	global_load_lds_dwordx4 v0, s[14:15]
	s_add_i32 m0, s30, 0x12000
	v_add_lshl_u32 v134, v3, v2, 1
	s_mul_hi_i32 s11, s46, 0x160000
	s_add_u32 s12, s25, s12
	global_load_lds_dwordx4 v134, s[14:15]
	s_addc_u32 s13, s26, s11
	s_mov_b32 m0, s30
	s_add_i32 s31, s30, 0x2000
	global_load_lds_dwordx4 v130, s[12:13]
	s_mov_b32 m0, s31
	s_add_u32 s18, s14, 0xb0000
	global_load_lds_dwordx4 v132, s[12:13]
	s_addc_u32 s19, s15, 0
	s_add_i32 m0, s30, 0x14000
	v_mov_b32_e32 v135, v1
	global_load_lds_dwordx4 v0, s[18:19]
	s_add_i32 m0, s30, 0x16000
	v_mov_b32_e32 v131, v1
	global_load_lds_dwordx4 v134, s[18:19]
	s_add_u32 s18, s12, 0xb0000
	s_addc_u32 s19, s13, 0
	s_add_i32 s34, s30, 0x4000
	s_mov_b32 m0, s34
	s_add_i32 s35, s30, 0x6000
	global_load_lds_dwordx4 v130, s[18:19]
	s_mov_b32 m0, s35
	v_mov_b32_e32 v133, v1
	global_load_lds_dwordx4 v132, s[18:19]
	s_mov_b32 s60, s44
	v_lshl_add_u64 v[8:9], s[14:15], 0, v[0:1]
	v_lshl_add_u64 v[6:7], s[14:15], 0, v[134:135]
	v_lshl_add_u64 v[4:5], s[12:13], 0, v[130:131]
	s_cmp_lg_u32 s9, 1
	v_lshl_add_u64 v[2:3], s[12:13], 0, v[132:133]
	s_setprio 1
	s_cbranch_scc1 .LBB0_103
	s_barrier
	s_setprio 0

.LBB0_168:
	s_cmp_lt_i32 s57, 7
	s_mov_b64 s[2:3], -1
	s_mov_b32 s66, s56
	s_cbranch_scc1 .LBB0_270
	s_cmp_gt_i32 s57, 7
	s_cbranch_scc0 .LBB0_183
	s_add_i32 s1, s86, -13
	s_cmp_lt_u32 s1, 12
	s_cselect_b32 s1, 0x80, s17
	s_mul_i32 s76, s1, 22
	s_cmp_ge_i32 s0, s76
	v_readfirstlane_b32 s26, v158
	s_cbranch_scc1 .LBB0_182
	v_lshlrev_b32_e32 v0, 4, v158
	s_waitcnt vmcnt(0)
	v_add_u32_e32 v2, 0x2000, v0
	v_ashrrev_i32_e32 v3, 31, v2
	v_lshrrev_b32_e32 v3, 22, v3
	v_add_u32_e32 v3, v2, v3
	v_ashrrev_i32_e32 v10, 10, v3
	v_mul_i32_i24_e32 v3, 0x400, v10
	v_sub_u32_e32 v2, v2, v3
	v_lshrrev_b32_e32 v3, 4, v2
	v_bitop3_b32 v2, v3, v2, 32 bitop3:0x6c
	s_load_dwordx2 s[2:3], s[54:55], 0x118
	v_ashrrev_i32_e32 v3, 31, v2
	v_lshrrev_b32_e32 v3, 26, v3
	v_add_u32_e32 v3, v2, v3
	v_lshlrev_b32_e32 v4, 3, v10
	s_mov_b32 s10, s44
	v_ashrrev_i32_e32 v11, 6, v3
	v_and_b32_e32 v4, -16, v4
	s_mul_i32 s9, s10, 0xb00000
	v_add_u32_e32 v4, v11, v4
	s_load_dwordx4 s[44:47], s[54:55], 0x158
	s_waitcnt lgkmcnt(0)
	s_add_u32 s27, s2, s9
	v_and_b32_e32 v5, 3, v11
	s_mov_b32 s2, 0x1fffe0
	v_lshrrev_b32_e32 v6, 2, v4
	v_lshlrev_b32_e32 v7, 1, v4
	v_and_b32_e32 v3, 0xc0, v3
	v_and_or_b32 v5, v4, s2, v5
	v_and_b32_e32 v6, 4, v6
	v_and_b32_e32 v7, 24, v7
	v_sub_u32_e32 v2, v2, v3
	v_or3_b32 v5, v5, v6, v7
	v_lshlrev_b32_e32 v6, 5, v10
	v_ashrrev_i16_sdwa v2, v207, sext(v2) dst_sel:DWORD dst_unused:UNUSED_PAD src0_sel:DWORD src1_sel:BYTE_0
	v_and_b32_e32 v6, 32, v6
	v_bfe_i32 v12, v2, 0, 16
	v_add_lshl_u32 v2, v6, v12, 1
	v_lshl_add_u32 v130, v5, 11, v2
	v_lshl_add_u32 v132, v4, 11, v2
	v_bfe_i32 v2, v158, 27, 1
	v_lshrrev_b32_e32 v2, 22, v2
	v_add_u32_e32 v2, v0, v2
	v_and_b32_e32 v2, 0xfffffc00, v2
	v_sub_u32_e32 v0, v0, v2
	v_lshrrev_b32_e32 v2, 4, v0
	v_bitop3_b32 v2, v2, v0, 32 bitop3:0x6c
	v_ashrrev_i32_e32 v0, 31, v0
	v_lshrrev_b32_e32 v0, 26, v0
	v_add_u32_e32 v0, v2, v0
	v_ashrrev_i32_e32 v13, 6, v0
	v_ashrrev_i32_e32 v0, 31, v158
	v_lshrrev_b32_e32 v0, 26, v0
	v_add_u32_e32 v0, v158, v0
	v_ashrrev_i32_e32 v14, 6, v0
	v_lshlrev_b32_e32 v0, 3, v14
	s_mul_hi_i32 s8, s10, 0xb00000
	v_and_b32_e32 v0, -16, v0
	s_addc_u32 s28, s3, s8
	v_add_u32_e32 v3, v13, v0
	v_and_b32_e32 v0, 3, v13
	s_ashr_i32 s31, s0, 31
	v_and_or_b32 v0, v3, s2, v0
	s_lshr_b32 s2, s31, 29
	s_add_i32 s2, s0, s2
	s_ashr_i32 s9, s26, 6
	s_lshr_b32 s30, s76, 3
	s_ashr_i32 s3, s2, 3
	s_and_b32 s2, s2, -8
	s_mov_b32 s62, s10
	s_ashr_i32 s10, s26, 8
	s_lshl_b32 s29, s9, 10
	s_sub_i32 s2, s0, s2
	s_add_i32 s34, s30, 1
	s_cmp_lt_i32 s2, 0
	s_cselect_b32 s8, s34, s30
	s_mul_i32 s2, s8, s2
	s_add_i32 s2, s2, s3
	s_mul_hi_i32 s3, s2, 0x2e8ba2e9
	v_lshrrev_b32_e32 v4, 2, v3
	v_lshlrev_b32_e32 v5, 1, v3
	s_lshr_b32 s8, s3, 31
	s_ashr_i32 s3, s3, 5
	v_and_b32_e32 v4, 4, v4
	v_and_b32_e32 v5, 24, v5
	s_add_i32 s3, s3, s8
	v_or3_b32 v0, v0, v4, v5
	v_mul_i32_i24_e32 v5, 64, v13
	s_lshl_b32 s11, s3, 3
	v_sub_u32_e32 v2, v2, v5
	s_sub_i32 s8, s1, s11
	v_lshlrev_b32_e32 v4, 5, v14
	v_ashrrev_i16_sdwa v2, v207, sext(v2) dst_sel:DWORD dst_unused:UNUSED_PAD src0_sel:DWORD src1_sel:BYTE_0
	s_min_u32 s12, s8, 8
	s_mulk_i32 s3, 0xb0
	v_and_b32_e32 v4, 32, v4
	v_bfe_i32 v15, v2, 0, 16
	s_sub_i32 s13, s2, s3
	v_cvt_f32_ubyte0_e32 v5, s12
	v_add_lshl_u32 v2, v4, v15, 1
	v_cvt_f32_i32_e32 v4, s13
	v_rcp_iflag_f32_e32 v6, v5
	v_lshl_add_u32 v0, v0, 11, v2
	v_lshl_add_u32 v134, v3, 11, v2
	s_ashr_i32 s2, s13, 30
	v_mul_f32_e32 v2, v4, v6
	v_trunc_f32_e32 v2, v2
	v_fma_f32 v3, -v2, v5, v4
	v_cvt_i32_f32_e32 v2, v2
	s_or_b32 s8, s2, 1
	v_cmp_ge_f32_e64 s[2:3], |v3|, v5
	s_and_b64 s[2:3], s[2:3], exec
	s_cselect_b32 s2, s8, 0
	v_readfirstlane_b32 s3, v2
	s_add_i32 s8, s3, s2
	s_mul_i32 s2, s8, s12
	s_sub_i32 s2, s13, s2
	s_sext_i32_i16 s2, s2
	s_add_i32 s2, s11, s2
	s_ashr_i32 s3, s2, 31
	s_bfe_i64 s[14:15], s[8:9], 0x100000
	s_lshl_b64 s[12:13], s[2:3], 19
	s_lshl_b64 s[14:15], s[14:15], 19
	s_add_u32 s18, s27, s14
	s_addc_u32 s19, s28, s15
	s_add_i32 s3, s29, 0
	s_add_i32 m0, s3, 0x10000
	v_mov_b32_e32 v131, v1
	global_load_lds_dwordx4 v0, s[18:19]
	s_add_i32 m0, s3, 0x12000
	s_add_u32 s22, s44, s12
	global_load_lds_dwordx4 v130, s[18:19]
	s_addc_u32 s23, s45, s13
	s_mov_b32 m0, s3
	s_add_i32 s35, s3, 0x2000
	global_load_lds_dwordx4 v134, s[22:23]
	s_mov_b32 m0, s35
	s_add_u32 s12, s18, 0x40000
	global_load_lds_dwordx4 v132, s[22:23]
	s_addc_u32 s13, s19, 0
	s_add_i32 m0, s3, 0x14000
	v_mov_b32_e32 v135, v1
	global_load_lds_dwordx4 v0, s[12:13]
	s_add_i32 m0, s3, 0x16000
	v_mov_b32_e32 v133, v1
	global_load_lds_dwordx4 v130, s[12:13]
	s_add_u32 s12, s22, 0x40000
	s_addc_u32 s13, s23, 0
	s_add_i32 s38, s3, 0x4000
	s_mov_b32 m0, s38
	s_add_i32 s39, s3, 0x6000
	global_load_lds_dwordx4 v134, s[12:13]
	s_mov_b32 m0, s39
	s_mov_b32 s60, s57
	global_load_lds_dwordx4 v132, s[12:13]
	v_lshl_add_u64 v[8:9], s[18:19], 0, v[0:1]
	v_lshl_add_u64 v[6:7], s[18:19], 0, v[130:131]
	v_lshl_add_u64 v[4:5], s[22:23], 0, v[134:135]
	s_cmp_lg_u32 s10, 1
	v_lshl_add_u64 v[2:3], s[22:23], 0, v[132:133]
	s_setprio 1
	s_cbranch_scc1 .LBB0_173
	s_barrier
	s_setprio 0

.LBB0_192:
	v_ashrrev_i32_e32 v0, 31, v158
	v_lshrrev_b32_e32 v0, 26, v0
	v_add_u32_e32 v0, v158, v0
	s_waitcnt vmcnt(0)
	v_ashrrev_i32_e32 v10, 6, v0
	v_bfe_i32 v0, v158, 27, 1
	v_lshlrev_b32_e32 v2, 4, v158
	v_lshrrev_b32_e32 v0, 22, v0
	v_add_u32_e32 v0, v2, v0
	v_and_b32_e32 v0, 0xfffffc00, v0
	v_sub_u32_e32 v0, v2, v0
	v_lshrrev_b32_e32 v3, 4, v0
	v_bitop3_b32 v3, v3, v0, 32 bitop3:0x6c
	v_ashrrev_i32_e32 v0, 31, v0
	v_lshrrev_b32_e32 v0, 26, v0
	v_add_u32_e32 v0, v3, v0
	v_ashrrev_i32_e32 v11, 6, v0
	v_lshlrev_b32_e32 v4, 3, v10
	v_mul_i32_i24_e32 v5, 64, v11
	v_and_b32_e32 v4, -16, v4
	v_sub_u32_e32 v3, v3, v5
	v_add_u32_e32 v0, v11, v4
	v_ashrrev_i16_sdwa v3, v207, sext(v3) dst_sel:DWORD dst_unused:UNUSED_PAD src0_sel:DWORD src1_sel:BYTE_0
	v_lshlrev_b32_e32 v4, 5, v10
	v_bfe_i32 v12, v3, 0, 16
	v_lshlrev_b32_e32 v3, 1, v0
	v_lshrrev_b32_e32 v5, 2, v0
	v_and_b32_e32 v6, 3, v11
	s_mov_b32 s14, 0x1fffe0
	v_and_b32_e32 v4, 32, v4
	v_and_b32_e32 v3, 24, v3
	v_and_b32_e32 v5, 4, v5
	v_and_or_b32 v6, v0, s14, v6
	v_or3_b32 v3, v6, v5, v3
	v_add_lshl_u32 v4, v4, v12, 1
	v_add_u32_e32 v2, 0x2000, v2
	v_lshl_add_u32 v130, v0, 11, v4
	v_lshl_add_u32 v0, v3, 11, v4
	v_ashrrev_i32_e32 v3, 31, v2
	v_lshrrev_b32_e32 v3, 22, v3
	v_add_u32_e32 v3, v2, v3
	v_ashrrev_i32_e32 v13, 10, v3
	v_mul_i32_i24_e32 v3, 0x400, v13
	v_sub_u32_e32 v2, v2, v3
	v_lshrrev_b32_e32 v3, 4, v2
	v_bitop3_b32 v2, v3, v2, 32 bitop3:0x6c
	v_ashrrev_i32_e32 v4, 31, v2
	v_lshrrev_b32_e32 v4, 26, v4
	v_lshlrev_b32_e32 v3, 3, v13
	v_add_u32_e32 v4, v2, v4
	v_and_b32_e32 v3, -16, v3
	v_ashrrev_i32_e32 v14, 6, v4
	s_waitcnt lgkmcnt(0)
	s_add_u32 s46, s18, 0x4000000
	v_add_u32_e32 v3, v14, v3
	v_and_b32_e32 v6, 3, v14
	s_addc_u32 s47, s19, 0
	v_and_or_b32 v6, v3, s14, v6
	s_ashr_i32 s14, s24, 3
	s_add_i32 s14, s25, s14
	s_ashr_i32 s15, s14, 31
	v_and_b32_e32 v4, 0xc0, v4
	s_lshr_b32 s15, s15, 27
	v_sub_u32_e32 v2, v2, v4
	s_add_i32 s15, s14, s15
	v_ashrrev_i16_sdwa v2, v207, sext(v2) dst_sel:DWORD dst_unused:UNUSED_PAD src0_sel:DWORD src1_sel:BYTE_0
	s_ashr_i32 s18, s15, 5
	v_lshlrev_b32_e32 v5, 5, v13
	v_bfe_i32 v15, v2, 0, 16
	v_lshlrev_b32_e32 v2, 1, v3
	v_lshrrev_b32_e32 v4, 2, v3
	s_lshl_b32 s18, s18, 3
	v_and_b32_e32 v5, 32, v5
	v_and_b32_e32 v2, 24, v2
	v_and_b32_e32 v4, 4, v4
	s_sub_i32 s19, 4, s18
	v_or3_b32 v2, v6, v4, v2
	v_add_lshl_u32 v4, v5, v15, 1
	s_min_u32 s19, s19, 8
	s_andn2_b32 s15, s15, 31
	v_lshl_add_u32 v132, v3, 11, v4
	s_sub_i32 s24, s14, s15
	v_cvt_f32_ubyte0_e32 v3, s19
	v_lshl_add_u32 v134, v2, 11, v4
	v_cvt_f32_i32_e32 v2, s24
	v_rcp_iflag_f32_e32 v4, v3
	s_ashr_i32 s22, s1, 6
	s_ashr_i32 s14, s24, 30
	s_ashr_i32 s23, s1, 8
	v_mul_f32_e32 v4, v2, v4
	v_trunc_f32_e32 v4, v4
	v_fma_f32 v2, -v4, v3, v2
	v_cvt_i32_f32_e32 v4, v4
	s_lshl_b32 s48, s22, 10
	s_or_b32 s25, s14, 1
	v_cmp_ge_f32_e64 s[14:15], |v2|, v3
	s_and_b64 s[14:15], s[14:15], exec
	s_cselect_b32 s14, s25, 0
	v_readfirstlane_b32 s15, v4
	s_add_i32 s14, s15, s14
	s_mul_i32 s15, s14, s19
	s_sub_i32 s15, s24, s15
	s_sext_i32_i8 s15, s15
	s_add_i32 s18, s18, s15
	s_ashr_i32 s19, s18, 31
	s_bfe_i64 s[26:27], s[14:15], 0x80000
	s_lshl_b64 s[24:25], s[18:19], 19
	s_lshl_b64 s[26:27], s[26:27], 19
	s_add_u32 s34, s12, s26
	s_addc_u32 s35, s13, s27
	s_add_i32 s19, s48, 0
	s_add_i32 m0, s19, 0x10000
	v_mov_b32_e32 v135, v1
	global_load_lds_dwordx4 v0, s[34:35]
	s_add_i32 m0, s19, 0x12000
	s_add_u32 s44, s46, s24
	global_load_lds_dwordx4 v134, s[34:35]
	s_addc_u32 s45, s47, s25
	s_mov_b32 m0, s19
	s_add_i32 s49, s19, 0x2000
	global_load_lds_dwordx4 v130, s[44:45]
	s_mov_b32 m0, s49
	s_add_u32 s24, s34, 0x40000
	global_load_lds_dwordx4 v132, s[44:45]
	s_addc_u32 s25, s35, 0
	s_add_i32 m0, s19, 0x14000
	v_mov_b32_e32 v131, v1
	global_load_lds_dwordx4 v0, s[24:25]
	s_add_i32 m0, s19, 0x16000
	v_mov_b32_e32 v133, v1
	global_load_lds_dwordx4 v134, s[24:25]
	s_add_u32 s24, s44, 0x40000
	s_addc_u32 s25, s45, 0
	s_add_i32 s50, s19, 0x4000
	s_mov_b32 m0, s50
	s_add_i32 s51, s19, 0x6000
	global_load_lds_dwordx4 v130, s[24:25]
	s_mov_b32 m0, s51
	v_lshl_add_u64 v[8:9], s[34:35], 0, v[0:1]
	global_load_lds_dwordx4 v132, s[24:25]
	v_lshl_add_u64 v[6:7], s[34:35], 0, v[134:135]
	v_lshl_add_u64 v[4:5], s[44:45], 0, v[130:131]
	s_cmp_lg_u32 s23, 1
	v_lshl_add_u64 v[2:3], s[44:45], 0, v[132:133]
	s_setprio 1
	s_cbranch_scc1 .LBB0_194
	s_barrier
	s_setprio 0

.LBB0_239:
	v_lshrrev_b32_e32 v0, 26, v159
	v_add_u32_e32 v0, v158, v0
	v_ashrrev_i32_e32 v10, 6, v0
	v_bfe_i32 v0, v158, 27, 1
	v_lshlrev_b32_e32 v2, 4, v158
	v_lshrrev_b32_e32 v0, 22, v0
	v_add_u32_e32 v0, v2, v0
	v_and_b32_e32 v0, 0xfffffc00, v0
	v_sub_u32_e32 v0, v2, v0
	v_lshrrev_b32_e32 v3, 4, v0
	v_bitop3_b32 v3, v3, v0, 32 bitop3:0x6c
	v_ashrrev_i32_e32 v0, 31, v0
	v_lshrrev_b32_e32 v0, 26, v0
	v_lshlrev_b32_e32 v4, 3, v10
	v_add_u32_e32 v0, v3, v0
	v_and_b32_e32 v4, -16, v4
	v_ashrrev_i32_e32 v11, 6, v0
	v_add_u32_e32 v0, v11, v4
	v_lshlrev_b32_e32 v4, 5, v10
	v_and_b32_e32 v12, 32, v4
	v_mul_i32_i24_e32 v4, 64, v11
	v_sub_u32_e32 v3, v3, v4
	s_add_u32 s29, s2, 0x16580000
	v_ashrrev_i16_sdwa v3, v207, sext(v3) dst_sel:DWORD dst_unused:UNUSED_PAD src0_sel:DWORD src1_sel:BYTE_0
	v_lshlrev_b32_e32 v4, 1, v0
	v_lshrrev_b32_e32 v5, 2, v0
	v_and_b32_e32 v6, 3, v11
	s_mov_b32 s2, 0xffffe0
	v_bfe_i32 v13, v3, 0, 16
	v_and_b32_e32 v4, 24, v4
	v_and_b32_e32 v5, 4, v5
	v_and_or_b32 v6, v0, s2, v6
	v_add_u32_e32 v3, v12, v13
	v_or3_b32 v4, v6, v5, v4
	v_mul_lo_u32 v0, v0, s71
	v_add_lshl_u32 v130, v3, v0, 1
	v_mul_u32_u24_e32 v0, 0xb00, v4
	v_add_u32_e32 v2, 0x2000, v2
	v_add_lshl_u32 v0, v0, v3, 1
	v_ashrrev_i32_e32 v3, 31, v2
	v_lshrrev_b32_e32 v3, 22, v3
	v_add_u32_e32 v3, v2, v3
	v_ashrrev_i32_e32 v14, 10, v3
	v_mul_i32_i24_e32 v3, 0x400, v14
	v_sub_u32_e32 v2, v2, v3
	v_lshrrev_b32_e32 v3, 4, v2
	v_bitop3_b32 v2, v3, v2, 32 bitop3:0x6c
	v_ashrrev_i32_e32 v4, 31, v2
	v_lshrrev_b32_e32 v4, 26, v4
	v_lshlrev_b32_e32 v3, 3, v14
	v_add_u32_e32 v4, v2, v4
	v_and_b32_e32 v3, -16, v3
	v_ashrrev_i32_e32 v15, 6, v4
	v_add_u32_e32 v3, v15, v3
	v_and_b32_e32 v6, 3, v15
	s_addc_u32 s30, s3, 0
	v_and_or_b32 v6, v3, s2, v6
	s_ashr_i32 s2, s14, 3
	s_add_i32 s2, s15, s2
	s_ashr_i32 s3, s2, 31
	v_and_b32_e32 v4, 0xc0, v4
	s_lshr_b32 s3, s3, 27
	v_lshlrev_b32_e32 v5, 5, v14
	v_sub_u32_e32 v2, v2, v4
	s_add_i32 s3, s2, s3
	v_and_b32_e32 v16, 32, v5
	v_ashrrev_i16_sdwa v2, v207, sext(v2) dst_sel:DWORD dst_unused:UNUSED_PAD src0_sel:DWORD src1_sel:BYTE_0
	v_lshlrev_b32_e32 v4, 1, v3
	v_lshrrev_b32_e32 v5, 2, v3
	s_ashr_i32 s14, s3, 5
	v_bfe_i32 v17, v2, 0, 16
	v_and_b32_e32 v4, 24, v4
	v_and_b32_e32 v5, 4, v5
	s_lshl_b32 s14, s14, 3
	v_add_u32_e32 v2, v16, v17
	v_or3_b32 v4, v6, v5, v4
	v_mul_lo_u32 v3, v3, s71
	s_sub_i32 s15, 4, s14
	v_add_lshl_u32 v132, v2, v3, 1
	v_mul_u32_u24_e32 v3, 0xb00, v4
	s_min_u32 s15, s15, 8
	s_andn2_b32 s3, s3, 31
	v_add_lshl_u32 v134, v3, v2, 1
	s_sub_i32 s18, s2, s3
	v_cvt_f32_ubyte0_e32 v3, s15
	v_cvt_f32_i32_e32 v2, s18
	v_rcp_iflag_f32_e32 v4, v3
	s_ashr_i32 s12, s28, 6
	s_ashr_i32 s2, s18, 30
	s_ashr_i32 s13, s28, 8
	v_mul_f32_e32 v4, v2, v4
	v_trunc_f32_e32 v4, v4
	v_fma_f32 v2, -v4, v3, v2
	v_cvt_i32_f32_e32 v4, v4
	s_lshl_b32 s31, s12, 10
	s_or_b32 s19, s2, 1
	v_cmp_ge_f32_e64 s[2:3], |v2|, v3
	s_and_b64 s[2:3], s[2:3], exec
	s_cselect_b32 s2, s19, 0
	v_readfirstlane_b32 s3, v4
	s_add_i32 s2, s3, s2
	s_mul_i32 s3, s2, s15
	s_sub_i32 s3, s18, s3
	s_sext_i32_i8 s3, s3
	s_mov_b32 s52, s44
	s_add_i32 s44, s14, s3
	s_mul_hi_i32 s3, s44, 0x160000
	s_bfe_i64 s[14:15], s[2:3], 0x80000
	s_mul_hi_i32 s15, s14, 0x160000
	s_mul_i32 s14, s14, 0x160000
	s_waitcnt lgkmcnt(0)
	s_add_u32 s22, s8, s14
	s_addc_u32 s23, s9, s15
	s_add_i32 s34, s31, 0
	s_add_i32 m0, s34, 0x10000
	s_mul_i32 s18, s44, 0x160000
	global_load_lds_dwordx4 v0, s[22:23]
	s_add_i32 m0, s34, 0x12000
	s_add_u32 s18, s29, s18
	global_load_lds_dwordx4 v134, s[22:23]
	s_addc_u32 s19, s30, s3
	s_mov_b32 m0, s34
	s_add_i32 s35, s34, 0x2000
	global_load_lds_dwordx4 v130, s[18:19]
	s_mov_b32 m0, s35
	s_add_u32 s14, s22, 0xb0000
	global_load_lds_dwordx4 v132, s[18:19]
	s_addc_u32 s15, s23, 0
	s_add_i32 m0, s34, 0x14000
	v_mov_b32_e32 v135, v1
	global_load_lds_dwordx4 v0, s[14:15]
	s_add_i32 m0, s34, 0x16000
	v_mov_b32_e32 v131, v1
	global_load_lds_dwordx4 v134, s[14:15]
	s_add_u32 s14, s18, 0xb0000
	s_addc_u32 s15, s19, 0
	s_add_i32 s38, s34, 0x4000
	s_mov_b32 m0, s38
	s_add_i32 s39, s34, 0x6000
	global_load_lds_dwordx4 v130, s[14:15]
	s_mov_b32 m0, s39
	v_mov_b32_e32 v133, v1
	global_load_lds_dwordx4 v132, s[14:15]
	v_lshl_add_u64 v[8:9], s[22:23], 0, v[0:1]
	v_lshl_add_u64 v[6:7], s[22:23], 0, v[134:135]
	v_lshl_add_u64 v[4:5], s[18:19], 0, v[130:131]
	s_cmp_lg_u32 s13, 1
	v_lshl_add_u64 v[2:3], s[18:19], 0, v[132:133]
	s_setprio 1
	s_cbranch_scc1 .LBB0_241
	s_barrier
	s_setprio 0

.LBB0_276:
	v_ashrrev_i32_e32 v0, 31, v158
	v_lshrrev_b32_e32 v0, 26, v0
	v_add_u32_e32 v0, v158, v0
	s_waitcnt vmcnt(0)
	v_ashrrev_i32_e32 v10, 6, v0
	v_bfe_i32 v0, v158, 27, 1
	v_lshlrev_b32_e32 v2, 4, v158
	v_lshrrev_b32_e32 v0, 22, v0
	v_add_u32_e32 v0, v2, v0
	v_and_b32_e32 v0, 0xfffffc00, v0
	v_sub_u32_e32 v0, v2, v0
	v_lshrrev_b32_e32 v3, 4, v0
	v_bitop3_b32 v3, v3, v0, 32 bitop3:0x6c
	v_ashrrev_i32_e32 v0, 31, v0
	v_lshrrev_b32_e32 v0, 26, v0
	v_add_u32_e32 v0, v3, v0
	v_ashrrev_i32_e32 v11, 6, v0
	v_lshlrev_b32_e32 v4, 3, v10
	v_mul_i32_i24_e32 v5, 64, v11
	s_ashr_i32 s15, s14, 31
	v_and_b32_e32 v4, -16, v4
	v_sub_u32_e32 v3, v3, v5
	s_ashr_i32 s12, s10, 3
	s_lshl_b64 s[8:9], s[14:15], 21
	v_add_u32_e32 v0, v11, v4
	v_ashrrev_i16_sdwa v3, v207, sext(v3) dst_sel:DWORD dst_unused:UNUSED_PAD src0_sel:DWORD src1_sel:BYTE_0
	s_waitcnt lgkmcnt(0)
	s_add_u32 s27, s2, s8
	v_lshlrev_b32_e32 v4, 5, v10
	v_bfe_i32 v12, v3, 0, 16
	v_lshlrev_b32_e32 v3, 1, v0
	v_lshrrev_b32_e32 v5, 2, v0
	v_and_b32_e32 v6, 3, v11
	s_mov_b32 s2, 0x1fffe0
	v_and_b32_e32 v4, 32, v4
	v_and_b32_e32 v3, 24, v3
	v_and_b32_e32 v5, 4, v5
	v_and_or_b32 v6, v0, s2, v6
	v_or3_b32 v3, v6, v5, v3
	v_add_lshl_u32 v4, v4, v12, 1
	v_add_u32_e32 v2, 0x2000, v2
	v_lshl_add_u32 v130, v0, 11, v4
	v_lshl_add_u32 v0, v3, 11, v4
	v_ashrrev_i32_e32 v3, 31, v2
	v_lshrrev_b32_e32 v3, 22, v3
	v_add_u32_e32 v3, v2, v3
	v_ashrrev_i32_e32 v13, 10, v3
	v_mul_i32_i24_e32 v3, 0x400, v13
	v_sub_u32_e32 v2, v2, v3
	v_lshrrev_b32_e32 v3, 4, v2
	v_bitop3_b32 v2, v3, v2, 32 bitop3:0x6c
	v_ashrrev_i32_e32 v4, 31, v2
	v_lshrrev_b32_e32 v4, 26, v4
	v_lshlrev_b32_e32 v3, 3, v13
	v_add_u32_e32 v4, v2, v4
	v_and_b32_e32 v3, -16, v3
	v_ashrrev_i32_e32 v14, 6, v4
	v_add_u32_e32 v3, v14, v3
	v_and_b32_e32 v6, 3, v14
	s_addc_u32 s28, s3, s9
	v_and_or_b32 v6, v3, s2, v6
	s_add_i32 s2, s11, s12
	s_ashr_i32 s3, s2, 31
	s_lshr_b32 s3, s3, 27
	s_add_i32 s3, s2, s3
	s_ashr_i32 s8, s3, 5
	s_and_b32 s3, s3, 0xffe0
	s_sub_i32 s2, s2, s3
	s_bfe_i32 s3, s2, 0x80000
	s_bfe_u32 s3, s3, 0x3000c
	s_add_i32 s3, s2, s3
	s_lshl_b32 s11, s8, 3
	s_bfe_i32 s8, s3, 0x80000
	s_and_b32 s3, s3, 0xf8
	s_sub_i32 s2, s2, s3
	s_sext_i32_i16 s8, s8
	s_sext_i32_i8 s2, s2
	s_ashr_i32 s9, s1, 6
	s_lshr_b32 s8, s8, 3
	s_add_i32 s2, s11, s2
	s_mov_b32 s60, s14
	v_and_b32_e32 v4, 0xc0, v4
	s_ashr_i32 s3, s2, 31
	s_bfe_i64 s[14:15], s[8:9], 0x100000
	v_sub_u32_e32 v2, v2, v4
	s_ashr_i32 s10, s1, 8
	s_lshl_b32 s29, s9, 10
	s_lshl_b64 s[12:13], s[2:3], 19
	s_lshl_b64 s[14:15], s[14:15], 19
	v_ashrrev_i16_sdwa v2, v207, sext(v2) dst_sel:DWORD dst_unused:UNUSED_PAD src0_sel:DWORD src1_sel:BYTE_0
	s_add_u32 s18, s27, s14
	v_lshlrev_b32_e32 v5, 5, v13
	v_bfe_i32 v15, v2, 0, 16
	v_lshlrev_b32_e32 v2, 1, v3
	v_lshrrev_b32_e32 v4, 2, v3
	s_addc_u32 s19, s28, s15
	s_add_i32 s3, s29, 0
	v_and_b32_e32 v5, 32, v5
	v_and_b32_e32 v2, 24, v2
	v_and_b32_e32 v4, 4, v4
	s_add_i32 m0, s3, 0x10000
	v_or3_b32 v2, v6, v4, v2
	v_add_lshl_u32 v4, v5, v15, 1
	global_load_lds_dwordx4 v0, s[18:19]
	s_add_i32 m0, s3, 0x12000
	v_lshl_add_u32 v134, v2, 11, v4
	s_add_u32 s22, s44, s12
	global_load_lds_dwordx4 v134, s[18:19]
	s_addc_u32 s23, s45, s13
	s_mov_b32 m0, s3
	s_add_i32 s30, s3, 0x2000
	v_lshl_add_u32 v132, v3, 11, v4
	global_load_lds_dwordx4 v130, s[22:23]
	s_mov_b32 m0, s30
	s_add_u32 s12, s18, 0x40000
	global_load_lds_dwordx4 v132, s[22:23]
	s_addc_u32 s13, s19, 0
	s_add_i32 m0, s3, 0x14000
	v_mov_b32_e32 v135, v1
	global_load_lds_dwordx4 v0, s[12:13]
	s_add_i32 m0, s3, 0x16000
	v_mov_b32_e32 v131, v1
	global_load_lds_dwordx4 v134, s[12:13]
	s_add_u32 s12, s22, 0x40000
	s_addc_u32 s13, s23, 0
	s_add_i32 s31, s3, 0x4000
	s_mov_b32 m0, s31
	s_add_i32 s34, s3, 0x6000
	global_load_lds_dwordx4 v130, s[12:13]
	s_mov_b32 m0, s34
	v_mov_b32_e32 v133, v1
	global_load_lds_dwordx4 v132, s[12:13]
	v_lshl_add_u64 v[8:9], s[18:19], 0, v[0:1]
	v_lshl_add_u64 v[6:7], s[18:19], 0, v[134:135]
	v_lshl_add_u64 v[4:5], s[22:23], 0, v[130:131]
	s_cmp_lg_u32 s10, 1
	v_lshl_add_u64 v[2:3], s[22:23], 0, v[132:133]
	s_setprio 1
	s_cbranch_scc1 .LBB0_278
	s_barrier
	s_setprio 0

.LBB0_664:
	s_and_b64 vcc, exec, s[2:3]
	s_cbranch_vccz .LBB0_677
	s_cmpk_gt_i32 s0, 0x62f
	v_readfirstlane_b32 s1, v158
	s_cbranch_scc1 .LBB0_677
	v_lshlrev_b32_e32 v0, 4, v158
	s_waitcnt vmcnt(0)
	v_add_u32_e32 v2, 0x2000, v0
	v_ashrrev_i32_e32 v3, 31, v2
	v_lshrrev_b32_e32 v3, 22, v3
	v_add_u32_e32 v3, v2, v3
	v_ashrrev_i32_e32 v10, 10, v3
	v_mul_i32_i24_e32 v3, 0x400, v10
	v_sub_u32_e32 v2, v2, v3
	v_lshrrev_b32_e32 v3, 4, v2
	v_bitop3_b32 v2, v3, v2, 32 bitop3:0x6c
	s_load_dwordx2 s[2:3], s[54:55], 0x108
	v_ashrrev_i32_e32 v3, 31, v2
	v_lshrrev_b32_e32 v3, 26, v3
	v_add_u32_e32 v3, v2, v3
	v_lshlrev_b32_e32 v4, 3, v10
	s_mov_b32 s10, s44
	v_ashrrev_i32_e32 v11, 6, v3
	v_and_b32_e32 v4, -16, v4
	s_mul_i32 s9, s10, 0x600000
	v_add_u32_e32 v4, v11, v4
	s_load_dwordx4 s[44:47], s[54:55], 0x158
	s_waitcnt lgkmcnt(0)
	s_add_u32 s26, s2, s9
	v_and_b32_e32 v5, 3, v11
	s_mov_b32 s2, 0x1fffe0
	v_lshrrev_b32_e32 v6, 2, v4
	v_lshlrev_b32_e32 v7, 1, v4
	v_and_b32_e32 v3, 0xc0, v3
	v_and_or_b32 v5, v4, s2, v5
	v_and_b32_e32 v6, 4, v6
	v_and_b32_e32 v7, 24, v7
	v_sub_u32_e32 v2, v2, v3
	v_or3_b32 v5, v5, v6, v7
	v_lshlrev_b32_e32 v6, 5, v10
	v_ashrrev_i16_sdwa v2, v207, sext(v2) dst_sel:DWORD dst_unused:UNUSED_PAD src0_sel:DWORD src1_sel:BYTE_0
	v_and_b32_e32 v6, 32, v6
	v_bfe_i32 v12, v2, 0, 16
	v_add_lshl_u32 v2, v6, v12, 1
	v_lshl_add_u32 v130, v5, 11, v2
	v_lshl_add_u32 v132, v4, 11, v2
	v_bfe_i32 v2, v158, 27, 1
	v_lshrrev_b32_e32 v2, 22, v2
	v_add_u32_e32 v2, v0, v2
	v_and_b32_e32 v2, 0xfffffc00, v2
	v_sub_u32_e32 v0, v0, v2
	v_lshrrev_b32_e32 v2, 4, v0
	v_bitop3_b32 v2, v2, v0, 32 bitop3:0x6c
	v_ashrrev_i32_e32 v0, 31, v0
	v_lshrrev_b32_e32 v0, 26, v0
	v_add_u32_e32 v0, v2, v0
	v_ashrrev_i32_e32 v13, 6, v0
	v_ashrrev_i32_e32 v0, 31, v158
	v_lshrrev_b32_e32 v0, 26, v0
	v_add_u32_e32 v0, v158, v0
	v_ashrrev_i32_e32 v14, 6, v0
	v_lshlrev_b32_e32 v0, 3, v14
	s_mul_hi_i32 s8, s10, 0x600000
	v_and_b32_e32 v0, -16, v0
	s_addc_u32 s27, s3, s8
	v_add_u32_e32 v3, v13, v0
	v_and_b32_e32 v0, 3, v13
	s_ashr_i32 s29, s0, 31
	v_and_or_b32 v0, v3, s2, v0
	s_lshr_b32 s2, s29, 29
	s_add_i32 s2, s0, s2
	s_ashr_i32 s10, s1, 6
	s_ashr_i32 s3, s2, 3
	s_and_b32 s2, s2, -8
	s_ashr_i32 s9, s1, 8
	s_lshl_b32 s28, s10, 10
	s_sub_i32 s2, s0, s2
	s_mov_b32 s59, s57
	s_cmp_lt_i32 s2, 0
	s_movk_i32 s57, 0xc7
	s_cselect_b32 s8, s57, 0xc6
	s_mul_i32 s2, s8, s2
	s_add_i32 s2, s2, s3
	s_mul_hi_i32 s3, s2, 0x2aaaaaab
	v_lshrrev_b32_e32 v4, 2, v3
	v_lshlrev_b32_e32 v5, 1, v3
	s_lshr_b32 s8, s3, 31
	s_ashr_i32 s3, s3, 4
	v_and_b32_e32 v4, 4, v4
	v_and_b32_e32 v5, 24, v5
	s_add_i32 s3, s3, s8
	v_or3_b32 v0, v0, v4, v5
	v_mul_i32_i24_e32 v5, 64, v13
	s_lshl_b32 s11, s3, 3
	v_sub_u32_e32 v2, v2, v5
	s_sub_i32 s8, 0x84, s11
	v_lshlrev_b32_e32 v4, 5, v14
	v_ashrrev_i16_sdwa v2, v207, sext(v2) dst_sel:DWORD dst_unused:UNUSED_PAD src0_sel:DWORD src1_sel:BYTE_0
	s_min_u32 s12, s8, 8
	s_mulk_i32 s3, 0x60
	v_and_b32_e32 v4, 32, v4
	v_bfe_i32 v15, v2, 0, 16
	s_sub_i32 s13, s2, s3
	v_cvt_f32_ubyte0_e32 v5, s12
	v_add_lshl_u32 v2, v4, v15, 1
	v_cvt_f32_i32_e32 v4, s13
	v_rcp_iflag_f32_e32 v6, v5
	v_lshl_add_u32 v0, v0, 11, v2
	v_lshl_add_u32 v134, v3, 11, v2
	s_ashr_i32 s2, s13, 30
	v_mul_f32_e32 v2, v4, v6
	v_trunc_f32_e32 v2, v2
	v_fma_f32 v3, -v2, v5, v4
	v_cvt_i32_f32_e32 v2, v2
	s_or_b32 s8, s2, 1
	v_cmp_ge_f32_e64 s[2:3], |v3|, v5
	s_and_b64 s[2:3], s[2:3], exec
	s_cselect_b32 s2, s8, 0
	v_readfirstlane_b32 s3, v2
	s_add_i32 s8, s3, s2
	s_mul_i32 s2, s8, s12
	s_sub_i32 s2, s13, s2
	s_sext_i32_i8 s2, s2
	s_add_i32 s2, s11, s2
	s_ashr_i32 s3, s2, 31
	s_bfe_i64 s[14:15], s[8:9], 0x80000
	s_lshl_b64 s[12:13], s[2:3], 19
	s_lshl_b64 s[14:15], s[14:15], 19
	s_add_u32 s18, s26, s14
	s_addc_u32 s19, s27, s15
	s_add_i32 s3, s28, 0
	s_add_i32 m0, s3, 0x10000
	v_mov_b32_e32 v131, v1
	global_load_lds_dwordx4 v0, s[18:19]
	s_add_i32 m0, s3, 0x12000
	s_add_u32 s22, s44, s12
	global_load_lds_dwordx4 v130, s[18:19]
	s_addc_u32 s23, s45, s13
	s_mov_b32 m0, s3
	s_add_i32 s30, s3, 0x2000
	global_load_lds_dwordx4 v134, s[22:23]
	s_mov_b32 m0, s30
	s_add_u32 s12, s18, 0x40000
	global_load_lds_dwordx4 v132, s[22:23]
	s_addc_u32 s13, s19, 0
	s_add_i32 m0, s3, 0x14000
	v_mov_b32_e32 v135, v1
	global_load_lds_dwordx4 v0, s[12:13]
	s_add_i32 m0, s3, 0x16000
	v_mov_b32_e32 v133, v1
	global_load_lds_dwordx4 v130, s[12:13]
	s_add_u32 s12, s22, 0x40000
	s_addc_u32 s13, s23, 0
	s_add_i32 s31, s3, 0x4000
	s_mov_b32 m0, s31
	s_add_i32 s34, s3, 0x6000
	global_load_lds_dwordx4 v134, s[12:13]
	s_mov_b32 m0, s34
	s_mov_b32 s60, s56
	global_load_lds_dwordx4 v132, s[12:13]
	v_lshl_add_u64 v[8:9], s[18:19], 0, v[0:1]
	v_lshl_add_u64 v[6:7], s[18:19], 0, v[130:131]
	v_lshl_add_u64 v[4:5], s[22:23], 0, v[134:135]
	s_cmp_lg_u32 s9, 1
	v_lshl_add_u64 v[2:3], s[22:23], 0, v[132:133]
	s_setprio 1
	s_cbranch_scc1 .LBB0_668
	s_barrier
	s_setprio 0
